# post2 row loop: five loop-invariant per-head norm-weight loads cached in registers (three fewer dependent round trips per row), on top of the union version
# speedup vs baseline: 1.0144x; 1.0010x over previous
; #define TIDX ((int)((wave_s << 6) | lane_id_v()))
; __device__ __forceinline__ float sum16(float v) { v += __shfl_xor(v, 1); v += __shfl_xor(v, 2); v += __shfl_xor(v, 4); v += __shfl_xor(v, 8); return v; }
; __device__ __forceinline__ void unpack8(const u32x4 w, float* x) { x[0] = bflo(w.x); x[1] = bfhi(w.x); x[2] = bflo(w.y); x[3] = bfhi(w.y); x[4] = bflo(w.z); x[5] = bfhi(w.z); x[6] = bflo(w.w); x[7] = bfhi(w.w); }
; __device__ __forceinline__ u32x4 pack8(const float* x) { u32x4 w; w.x = pk2(x[0], x[1]); w.y = pk2(x[2], x[3]); w.z = pk2(x[4], x[5]); w.w = pk2(x[6], x[7]); return w; }
; __device__ __forceinline__ void phase_post2(const Params& p, int layer, const int wave_s) {
;   int t_ = TIDX; asm volatile("" : "+v"(t_)); const int lane = t_ & 63, wave = __builtin_amdgcn_readfirstlane(t_ >> 6), gw = blockIdx.x * 8 + wave, NGW = gridDim.x * 8; (void)wave;
;   bf16_t* QC = (bf16_t*)(p.ws + WS_QC); const bf16_t* KVC = (const bf16_t*)(p.ws + WS_KVC); bf16_t* KC = (bf16_t*)(p.ws + WS_KC);
;   const float* cqn = p.c_q_norm + layer * 192; const float* ckn = p.c_k_norm + layer * 192;
;   const int h = lane >> 4, a = lane & 15;
;   for (int r = gw; r < LROWS; r += NGW) {
;     const float posf = (float)r;
;     { u32x4* ptr = (u32x4*)(QC + (size_t)r * 768 + h * 192 + a * 8); float x[8]; unpack8(*ptr, x); float ss = 0.f;
; #pragma unroll
;       for (int i = 0; i < 8; ++i) ss += x[i] * x[i];
;       const float rs = rsqrtf(sum16(ss) * (1.f / 128.f) + EPS) * QS_C;
; #pragma unroll
;       for (int i = 0; i < 8; ++i) x[i] = x[i] * rs * cqn[a * 8 + i];
;       *ptr = pack8(x); }
.LBB0_395:
	s_or_b64 exec, exec, s[0:1]
	s_waitcnt lgkmcnt(0)
	s_barrier
	v_mbcnt_lo_u32_b32 v0, -1, 0
	v_mbcnt_hi_u32_b32 v0, -1, v0
	s_nop 0
	v_or_b32_e32 v4, s61, v0
	s_nop 0
	v_readfirstlane_b32 s0, v4
	s_ashr_i32 s0, s0, 6
	s_add_i32 s28, s0, s75
	s_cmpk_gt_i32 s28, 0x400f
	s_cbranch_scc1 .LBB0_398
	v_lshlrev_b32_e32 v0, 4, v4
	v_readlane_b32 s0, v251, 0
	v_and_b32_e32 v0, 0x70, v0
	v_readlane_b32 s1, v251, 1
	s_mov_b32 s23, s5
	v_readlane_b32 s24, v254, 15
	v_readlane_b32 s26, v254, 17
	v_cmp_lt_i32_e32 vcc, v198, v197
	v_readlane_b32 s27, v254, 18
	global_load_dwordx4 v[0:3], v0, s[0:1] offset:328
	s_lshl_b64 s[0:1], s[22:23], 2
	s_add_u32 s2, s26, s0
	v_cndmask_b32_e32 v5, v196, v198, vcc
	v_cmp_lt_i32_e32 vcc, v199, v197
	s_addc_u32 s3, s27, s1
	v_lshlrev_b32_e32 v20, 2, v5
	v_cndmask_b32_e32 v5, v196, v199, vcc
	v_cmp_lt_i32_e32 vcc, v200, v197
	v_readlane_b32 s25, v254, 16
	s_add_u32 s0, s24, s0
	v_and_b32_e32 v12, 15, v4
	v_lshlrev_b32_e32 v21, 2, v5
	v_cndmask_b32_e32 v5, v196, v200, vcc
	v_cmp_lt_i32_e32 vcc, v201, v197
	s_addc_u32 s1, s25, s1
	v_bfe_u32 v10, v4, 4, 2
	v_lshlrev_b32_e32 v22, 2, v5
	v_cndmask_b32_e32 v5, v196, v201, vcc
	v_and_b32_e32 v4, 8, v4
	v_lshlrev_b32_e32 v168, 5, v12
	v_lshlrev_b32_e32 v14, 4, v12
	v_mov_b32_e32 v15, v169
	s_ashr_i32 s29, s28, 31
	v_lshlrev_b32_e32 v23, 2, v5
	v_cmp_eq_u32_e64 s[36:37], 0, v4
	v_lshl_add_u64 v[4:5], s[0:1], 0, v[168:169]
	v_lshl_add_u64 v[6:7], s[0:1], 0, v[14:15]
	s_lshl_b64 s[0:1], s[28:29], 11
	s_add_u32 s0, s0, 0x167a0000
	s_addc_u32 s1, s1, 0
	v_mul_u32_u24_e32 v16, 0xc0, v10
	v_lshlrev_b32_e32 v10, 9, v10
	v_mov_b32_e32 v11, s1
	s_mul_i32 s1, s28, 0x600
	v_lshl_add_u64 v[8:9], s[2:3], 0, v[168:169]
	v_or3_b32 v10, s0, v10, v14
	s_mul_hi_i32 s0, s28, 0x600
	s_add_u32 s2, s1, 0x14f40100
	s_addc_u32 s3, s0, 0
	v_lshl_or_b32 v12, v12, 3, s2
	v_mov_b32_e32 v13, s3
	v_lshlrev_b32_e32 v168, 1, v16
	v_or_b32_e32 v14, s1, v14
	v_mov_b32_e32 v15, s0
	v_readlane_b32 s0, v253, 51
	s_mov_b32 s2, 0x6dc9c883
	v_lshl_add_u64 v[12:13], v[12:13], 0, v[168:169]
	v_lshl_add_u64 v[14:15], v[14:15], 0, v[168:169]
	v_readlane_b32 s1, v253, 52
	s_mov_b32 s3, 0x3fc45f30
	global_load_dwordx4 v[100:103], v[4:5], off offset:16
	global_load_dwordx4 v[104:107], v[4:5], off
	global_load_dwordx4 v[108:111], v[6:7], off offset:512
	global_load_dwordx4 v[112:115], v[8:9], off offset:16
	global_load_dwordx4 v[116:119], v[8:9], off
	s_waitcnt vmcnt(0)
.LBB0_397:
	v_lshl_add_u64 v[16:17], s[78:79], 0, v[14:15]
	v_add_co_u32_e32 v18, vcc, 0x14f40000, v16
	v_cvt_f32_i32_e32 v62, s28
	s_nop 0
	v_addc_co_u32_e32 v19, vcc, 0, v17, vcc
	global_load_dwordx4 v[24:27], v[18:19], off
	s_add_i32 s28, s28, s80
	v_lshl_add_u64 v[14:15], v[14:15], 0, s[0:1]
	s_cmpk_lt_i32 s28, 0x4010
	s_waitcnt vmcnt(0)
	v_lshlrev_b32_e32 v36, 16, v24
	v_and_b32_e32 v24, 0xffff0000, v24
	v_lshlrev_b32_e32 v37, 16, v25
	v_and_b32_e32 v25, 0xffff0000, v25
	v_mov_b32_e32 v28, v36
	v_mov_b32_e32 v29, v24
	v_pk_mul_f32 v[38:39], v[28:29], v[28:29]
	v_mov_b32_e32 v28, v25
	v_mov_b32_e32 v29, v37
	v_pk_mul_f32 v[40:41], v[28:29], v[28:29]
	v_mov_b32_e32 v28, v100
	v_mov_b32_e32 v29, v101
	v_mov_b32_e32 v30, v102
	v_mov_b32_e32 v31, v103
	v_mov_b32_e32 v32, v104
	v_mov_b32_e32 v33, v105
	v_mov_b32_e32 v34, v106
	v_mov_b32_e32 v35, v107
	v_add_f32_e32 v38, v38, v39
	v_add_f32_e32 v38, v41, v38
	v_add_f32_e32 v38, v40, v38

; __device__ __forceinline__ void phase_post2(const Params& p, int layer, const int wave_s) {
;     ...
;       for (int i = 0; i < 8; ++i) x[i] = x[i] * rs * cqn[a * 8 + i];
	v_mov_b32_e32 v40, v28

; __device__ __forceinline__ float bflo(unsigned w) { return __uint_as_float(w << 16); }
; __device__ __forceinline__ float bfhi(unsigned w) { return __uint_as_float(w & 0xffff0000u); }
; __device__ __forceinline__ unsigned pk2(float lo, float hi) { return f2bf(lo) | (f2bf(hi) << 16); }
; __device__ __forceinline__ float sum16(float v) { v += __shfl_xor(v, 1); v += __shfl_xor(v, 2); v += __shfl_xor(v, 4); v += __shfl_xor(v, 8); return v; }
; __device__ __forceinline__ void unpack8(const u32x4 w, float* x) { x[0] = bflo(w.x); x[1] = bfhi(w.x); x[2] = bflo(w.y); x[3] = bfhi(w.y); x[4] = bflo(w.z); x[5] = bfhi(w.z); x[6] = bflo(w.w); x[7] = bfhi(w.w); }
; __device__ __forceinline__ u32x4 pack8(const float* x) { u32x4 w; w.x = pk2(x[0], x[1]); w.y = pk2(x[2], x[3]); w.z = pk2(x[4], x[5]); w.w = pk2(x[6], x[7]); return w; }
; __device__ __forceinline__ void phase_post2(const Params& p, int layer, const int wave_s) {
;     ...
;     { u32x4* ptr = (u32x4*)(QC + (size_t)r * 768 + h * 192 + a * 8); float x[8]; unpack8(*ptr, x); float ss = 0.f;
; #pragma unroll
;       for (int i = 0; i < 8; ++i) ss += x[i] * x[i];
;       const float rs = rsqrtf(sum16(ss) * (1.f / 128.f) + EPS) * QS_C;
; #pragma unroll
;       for (int i = 0; i < 8; ++i) x[i] = x[i] * rs * cqn[a * 8 + i];
;       *ptr = pack8(x); }
;     { u32x2* ptr = (u32x2*)(QC + (size_t)r * 768 + h * 192 + 128 + a * 4); const u32x2 w = *ptr; float x[4] = {bflo(w.x), bfhi(w.x), bflo(w.y), bfhi(w.y)};
;       const float rs = rsqrtf(sum16(x[0] * x[0] + x[1] * x[1] + x[2] * x[2] + x[3] * x[3]) * (1.f / 64.f) + EPS) * QS_C;
; #pragma unroll
;       for (int i = 0; i < 4; ++i) { const float y = x[i] * rs * cqn[128 + a * 4 + i]; const float other = __shfl_xor(y, 8);
;         float c, s; rope_cs(posf, p.inv_c[(a & 7) * 4 + i], c, s);
;         x[i] = (a & 8) ? other * s + y * c : y * c - other * s; }
;       *ptr = (u32x2){pk2(x[0], x[1]), pk2(x[2], x[3])}; }
	v_mov_b32_e32 v42, v32
	v_lshlrev_b32_e32 v32, 16, v26
	v_and_b32_e32 v26, 0xffff0000, v26
	v_mov_b32_e32 v44, v26
	v_mov_b32_e32 v45, v32
	v_mov_b32_e32 v41, v30
	v_mov_b32_e32 v30, v29
	v_lshl_add_u64 v[28:29], s[78:79], 0, v[12:13]
	v_pk_fma_f32 v[38:39], v[44:45], v[44:45], v[38:39] op_sel_hi:[1,1,0]
	global_load_dwordx2 v[44:45], v[28:29], off
	v_mul_f32_e32 v38, v0, v62
	v_cvt_f64_f32_e32 v[50:51], v38
	v_mul_f64 v[52:53], v[50:51], s[2:3]
	v_rndne_f64_e32 v[52:53], v[52:53]
	v_fma_f64 v[50:51], v[50:51], s[2:3], -v[52:53]
	v_cvt_f32_f64_e32 v38, v[50:51]
	v_sin_f32_e32 v50, v38
	v_cos_f32_e32 v52, v38
	v_mul_f32_e32 v38, v1, v62
	v_cvt_f64_f32_e32 v[54:55], v38
	v_mul_f64 v[56:57], v[54:55], s[2:3]
	v_rndne_f64_e32 v[56:57], v[56:57]
	v_fma_f64 v[54:55], v[54:55], s[2:3], -v[56:57]
	v_cvt_f32_f64_e32 v38, v[54:55]
	v_sin_f32_e32 v54, v38
	v_cos_f32_e32 v56, v38
	v_mul_f32_e32 v38, v2, v62
	v_cvt_f64_f32_e32 v[58:59], v38
	v_mul_f64 v[60:61], v[58:59], s[2:3]
	v_rndne_f64_e32 v[60:61], v[60:61]
	v_fma_f64 v[58:59], v[58:59], s[2:3], -v[60:61]
	v_cvt_f32_f64_e32 v38, v[58:59]
	v_sin_f32_e32 v51, v38
	v_cos_f32_e32 v53, v38
	v_mul_f32_e32 v38, v3, v62
	v_cvt_f64_f32_e32 v[58:59], v38
	v_mul_f64 v[60:61], v[58:59], s[2:3]
	v_rndne_f64_e32 v[60:61], v[60:61]
	v_fma_f64 v[58:59], v[58:59], s[2:3], -v[60:61]
	v_cvt_f32_f64_e32 v38, v[58:59]
	v_mov_b32_e32 v43, v34
	v_mov_b32_e32 v34, v33
	v_lshlrev_b32_e32 v33, 16, v27
	v_and_b32_e32 v27, 0xffff0000, v27
	v_pk_mul_f32 v[46:47], v[26:27], v[26:27]
	v_mov_b32_e32 v48, v27
	v_mov_b32_e32 v49, v33
	v_pk_mul_f32 v[48:49], v[48:49], v[48:49]
	v_sin_f32_e32 v55, v38
	v_cos_f32_e32 v57, v38
	v_mov_b32_e32 v65, v46
	v_mov_b32_e32 v47, v49
	v_lshl_add_u64 v[12:13], v[12:13], 0, s[0:1]
	s_waitcnt vmcnt(0)
	v_lshlrev_b32_e32 v58, 16, v44
	v_and_b32_e32 v44, 0xffff0000, v44
	v_lshlrev_b32_e32 v59, 16, v45
	v_and_b32_e32 v45, 0xffff0000, v45
	v_mov_b32_e32 v60, v58
	v_mov_b32_e32 v61, v44
	v_pk_mul_f32 v[60:61], v[60:61], v[60:61]
	v_mov_b32_e32 v62, v45
	v_mov_b32_e32 v63, v59
	v_pk_mul_f32 v[62:63], v[62:63], v[62:63]
	v_mov_b32_e32 v64, v60
	v_mov_b32_e32 v38, v61
	v_pk_add_f32 v[38:39], v[64:65], v[38:39]
	v_mov_b32_e32 v46, v63
	v_pk_add_f32 v[38:39], v[46:47], v[38:39]
	v_mov_b32_e32 v63, v48
	v_pk_add_f32 v[38:39], v[62:63], v[38:39]
	ds_bpermute_b32 v47, v20, v39
	ds_bpermute_b32 v46, v20, v38
	s_waitcnt lgkmcnt(0)
	v_pk_add_f32 v[38:39], v[38:39], v[46:47]
	ds_bpermute_b32 v47, v21, v39
	ds_bpermute_b32 v46, v21, v38
	s_waitcnt lgkmcnt(0)
	v_pk_add_f32 v[38:39], v[38:39], v[46:47]
	ds_bpermute_b32 v47, v22, v39
	ds_bpermute_b32 v46, v22, v38
	s_waitcnt lgkmcnt(0)
	v_pk_add_f32 v[38:39], v[38:39], v[46:47]
	ds_bpermute_b32 v47, v23, v39
	ds_bpermute_b32 v46, v23, v38
	s_waitcnt lgkmcnt(0)
	v_pk_add_f32 v[38:39], v[38:39], v[46:47]
	s_nop 0
	v_pk_fma_f32 v[38:39], v[38:39], s[64:65], v[170:171] op_sel_hi:[1,1,0]
	s_nop 0
	v_mul_f32_e32 v46, 0x4b800000, v39
	v_cmp_gt_f32_e64 s[38:39], s94, v39
	v_cmp_gt_f32_e32 vcc, s94, v38
	s_nop 0
	v_cndmask_b32_e64 v39, v39, v46, s[38:39]
	v_rsq_f32_e32 v39, v39
	s_nop 0
	v_mul_f32_e32 v46, 0x45800000, v39
	v_cndmask_b32_e64 v39, v39, v46, s[38:39]
	v_mul_f32_e32 v46, 0x3dd53b94, v39
	v_pk_mul_f32 v[24:25], v[46:47], v[24:25] op_sel_hi:[0,1]
	v_pk_mul_f32 v[26:27], v[46:47], v[26:27] op_sel_hi:[0,1]
	v_pk_mul_f32 v[36:37], v[46:47], v[36:37] op_sel_hi:[0,1]
	v_pk_mul_f32 v[24:25], v[34:35], v[24:25]
	v_pk_mul_f32 v[32:33], v[46:47], v[32:33] op_sel_hi:[0,1]
	v_pk_mul_f32 v[26:27], v[30:31], v[26:27]
	v_pk_mul_f32 v[36:37], v[42:43], v[36:37]
	v_pk_mul_f32 v[32:33], v[40:41], v[32:33]
	v_bfe_u32 v30, v27, 16, 1
	v_bfe_u32 v31, v26, 16, 1
	v_bfe_u32 v34, v25, 16, 1
	v_bfe_u32 v35, v24, 16, 1
	v_add3_u32 v24, v24, v35, s15
	v_add3_u32 v25, v25, v34, s15
	v_add3_u32 v26, v26, v31, s15
	v_add3_u32 v27, v27, v30, s15
	v_bfe_u32 v30, v36, 16, 1
	v_bfe_u32 v31, v37, 16, 1
	v_bfe_u32 v34, v32, 16, 1
	v_bfe_u32 v35, v33, 16, 1
	v_add3_u32 v33, v33, v35, s15
	v_add3_u32 v32, v32, v34, s15
	v_add3_u32 v31, v37, v31, s15
	v_add3_u32 v30, v36, v30, s15
	v_lshrrev_b32_e32 v30, 16, v30
	v_lshrrev_b32_e32 v31, 16, v31
	v_lshrrev_b32_e32 v32, 16, v32
	v_lshrrev_b32_e32 v33, 16, v33
	v_and_or_b32 v27, v27, s14, v33
	v_and_or_b32 v26, v26, s14, v32
	v_and_or_b32 v25, v25, s14, v31
	v_and_or_b32 v24, v24, s14, v30
	global_store_dwordx4 v[18:19], v[24:27], off
	s_nop 1
	v_mov_b32_e32 v24, v108
	v_mov_b32_e32 v25, v109
	v_mov_b32_e32 v26, v110
	v_mov_b32_e32 v27, v111
	v_mul_f32_e32 v18, 0x4b800000, v38
	v_cndmask_b32_e32 v18, v38, v18, vcc
	v_rsq_f32_e32 v18, v18

; __device__ __forceinline__ float bflo(unsigned w) { return __uint_as_float(w << 16); }
; __device__ __forceinline__ float bfhi(unsigned w) { return __uint_as_float(w & 0xffff0000u); }
; __device__ __forceinline__ unsigned pk2(float lo, float hi) { return f2bf(lo) | (f2bf(hi) << 16); }
; __device__ __forceinline__ float sum16(float v) { v += __shfl_xor(v, 1); v += __shfl_xor(v, 2); v += __shfl_xor(v, 4); v += __shfl_xor(v, 8); return v; }
; __device__ __forceinline__ void unpack8(const u32x4 w, float* x) { x[0] = bflo(w.x); x[1] = bfhi(w.x); x[2] = bflo(w.y); x[3] = bfhi(w.y); x[4] = bflo(w.z); x[5] = bfhi(w.z); x[6] = bflo(w.w); x[7] = bfhi(w.w); }
; __device__ __forceinline__ u32x4 pack8(const float* x) { u32x4 w; w.x = pk2(x[0], x[1]); w.y = pk2(x[2], x[3]); w.z = pk2(x[4], x[5]); w.w = pk2(x[6], x[7]); return w; }
; __device__ __forceinline__ void phase_post2(const Params& p, int layer, const int wave_s) {
;     ...
;     { u32x2* ptr = (u32x2*)(QC + (size_t)r * 768 + h * 192 + 128 + a * 4); const u32x2 w = *ptr; float x[4] = {bflo(w.x), bfhi(w.x), bflo(w.y), bfhi(w.y)};
;       const float rs = rsqrtf(sum16(x[0] * x[0] + x[1] * x[1] + x[2] * x[2] + x[3] * x[3]) * (1.f / 64.f) + EPS) * QS_C;
; #pragma unroll
;       for (int i = 0; i < 4; ++i) { const float y = x[i] * rs * cqn[128 + a * 4 + i]; const float other = __shfl_xor(y, 8);
;         float c, s; rope_cs(posf, p.inv_c[(a & 7) * 4 + i], c, s);
;         x[i] = (a & 8) ? other * s + y * c : y * c - other * s; }
;       *ptr = (u32x2){pk2(x[0], x[1]), pk2(x[2], x[3])}; }
;     { float x[8]; unpack8(*(const u32x4*)(KVC + (size_t)r * 1024 + h * 256 + a * 8), x); float ss = 0.f;
; #pragma unroll
;       for (int i = 0; i < 8; ++i) ss += x[i] * x[i];
;       const float rs = rsqrtf(sum16(ss) * (1.f / 128.f) + EPS);
; #pragma unroll
;       for (int i = 0; i < 8; ++i) x[i] = x[i] * rs * ckn[a * 8 + i];
;       *(u32x4*)(KC + (size_t)r * 768 + h * 192 + a * 8) = pack8(x); }
	v_mov_b32_e32 v32, v24
	v_mul_f32_e32 v19, 0x45800000, v18
	v_cndmask_b32_e32 v18, v18, v19, vcc
	v_mul_f32_e32 v18, 0x3dd53b94, v18
	v_pk_mul_f32 v[30:31], v[18:19], v[58:59] op_sel_hi:[0,1]
	v_mov_b32_e32 v33, v26
	v_pk_mul_f32 v[30:31], v[32:33], v[30:31]
	v_pk_mul_f32 v[18:19], v[18:19], v[44:45] op_sel_hi:[0,1]
	v_mov_b32_e32 v26, v25
	ds_bpermute_b32 v24, v23, v30
	v_pk_mul_f32 v[18:19], v[26:27], v[18:19]
	ds_bpermute_b32 v25, v23, v31
	ds_bpermute_b32 v26, v23, v18
	ds_bpermute_b32 v27, v23, v19
	s_waitcnt lgkmcnt(2)
	v_pk_mul_f32 v[24:25], v[50:51], v[24:25]
	s_nop 0
	v_cndmask_b32_e64 v25, v25, -v25, s[36:37]
	v_cndmask_b32_e64 v24, v24, -v24, s[36:37]
	s_waitcnt lgkmcnt(0)
	v_pk_mul_f32 v[26:27], v[54:55], v[26:27]
	v_pk_fma_f32 v[24:25], v[52:53], v[30:31], v[24:25]
	v_cndmask_b32_e64 v27, v27, -v27, s[36:37]
	v_cndmask_b32_e64 v26, v26, -v26, s[36:37]
	v_pk_fma_f32 v[18:19], v[56:57], v[18:19], v[26:27]
	v_and_b32_sdwa v26, v25, v171 dst_sel:DWORD dst_unused:UNUSED_PAD src0_sel:WORD_1 src1_sel:DWORD
	v_and_b32_sdwa v27, v24, v171 dst_sel:DWORD dst_unused:UNUSED_PAD src0_sel:WORD_1 src1_sel:DWORD
	v_add3_u32 v24, v24, v27, s15
	v_add3_u32 v25, v25, v26, s15
	v_and_b32_sdwa v26, v19, v171 dst_sel:DWORD dst_unused:UNUSED_PAD src0_sel:WORD_1 src1_sel:DWORD
	v_and_b32_sdwa v27, v18, v171 dst_sel:DWORD dst_unused:UNUSED_PAD src0_sel:WORD_1 src1_sel:DWORD
	v_add3_u32 v19, v19, v26, s15
	v_add3_u32 v18, v18, v27, s15
	v_and_b32_e32 v19, 0xffff0000, v19
	v_and_b32_e32 v18, 0xffff0000, v18
	v_or_b32_sdwa v19, v19, v25 dst_sel:DWORD dst_unused:UNUSED_PAD src0_sel:DWORD src1_sel:WORD_1
	v_or_b32_sdwa v18, v18, v24 dst_sel:DWORD dst_unused:UNUSED_PAD src0_sel:DWORD src1_sel:WORD_1
	global_store_dwordx2 v[28:29], v[18:19], off
	v_lshl_add_u64 v[18:19], s[78:79], 0, v[10:11]
	global_load_dwordx4 v[24:27], v[18:19], off
	v_lshl_add_u64 v[10:11], v[10:11], 0, s[66:67]
	s_waitcnt vmcnt(0)
	v_lshlrev_b32_e32 v19, 16, v25
	v_and_b32_e32 v25, 0xffff0000, v25
	v_mov_b32_e32 v28, v25
	v_mov_b32_e32 v29, v19
	v_pk_mul_f32 v[36:37], v[28:29], v[28:29]
	v_mov_b32_e32 v28, v112
	v_mov_b32_e32 v29, v113
	v_mov_b32_e32 v30, v114
	v_mov_b32_e32 v31, v115
	v_mov_b32_e32 v32, v116
	v_mov_b32_e32 v33, v117
	v_mov_b32_e32 v34, v118
	v_mov_b32_e32 v35, v119
	v_lshlrev_b32_e32 v18, 16, v24
	v_and_b32_e32 v24, 0xffff0000, v24
	v_mul_f32_e32 v44, v18, v18
	v_fmac_f32_e32 v44, v24, v24
	v_add_f32_e32 v37, v37, v44
	v_add_f32_e32 v36, v36, v37

; __device__ __forceinline__ float sum16(float v) { v += __shfl_xor(v, 1); v += __shfl_xor(v, 2); v += __shfl_xor(v, 4); v += __shfl_xor(v, 8); return v; }
; __device__ __forceinline__ void unpack8(const u32x4 w, float* x) { x[0] = bflo(w.x); x[1] = bfhi(w.x); x[2] = bflo(w.y); x[3] = bfhi(w.y); x[4] = bflo(w.z); x[5] = bfhi(w.z); x[6] = bflo(w.w); x[7] = bfhi(w.w); }
; __device__ __forceinline__ u32x4 pack8(const float* x) { u32x4 w; w.x = pk2(x[0], x[1]); w.y = pk2(x[2], x[3]); w.z = pk2(x[4], x[5]); w.w = pk2(x[6], x[7]); return w; }
; __device__ __forceinline__ void phase_post2(const Params& p, int layer, const int wave_s) {
;     ...
;     { float x[8]; unpack8(*(const u32x4*)(KVC + (size_t)r * 1024 + h * 256 + a * 8), x); float ss = 0.f;
; #pragma unroll
;       for (int i = 0; i < 8; ++i) ss += x[i] * x[i];
;       const float rs = rsqrtf(sum16(ss) * (1.f / 128.f) + EPS);
; #pragma unroll
;       for (int i = 0; i < 8; ++i) x[i] = x[i] * rs * ckn[a * 8 + i];
;       *(u32x4*)(KC + (size_t)r * 768 + h * 192 + a * 8) = pack8(x); }
	v_mov_b32_e32 v38, v32
	v_lshlrev_b32_e32 v32, 16, v26
	v_and_b32_e32 v26, 0xffff0000, v26
	v_mov_b32_e32 v40, v26
	v_mov_b32_e32 v41, v32
	v_mov_b32_e32 v39, v34
	v_mov_b32_e32 v34, v33
	v_lshlrev_b32_e32 v33, 16, v27
	v_and_b32_e32 v27, 0xffff0000, v27
	v_pk_mul_f32 v[40:41], v[40:41], v[40:41]
	v_mov_b32_e32 v42, v27
	v_mov_b32_e32 v43, v33
	v_add_f32_e32 v36, v41, v36
	v_pk_mul_f32 v[42:43], v[42:43], v[42:43]
	v_add_f32_e32 v36, v40, v36
	v_add_f32_e32 v36, v43, v36
	v_add_f32_e32 v36, v42, v36
	ds_bpermute_b32 v37, v20, v36
	s_waitcnt lgkmcnt(0)
	v_add_f32_e32 v36, v36, v37
	ds_bpermute_b32 v37, v21, v36
	s_waitcnt lgkmcnt(0)
	v_add_f32_e32 v36, v36, v37
	ds_bpermute_b32 v37, v22, v36
	s_waitcnt lgkmcnt(0)
	v_add_f32_e32 v36, v36, v37
	ds_bpermute_b32 v37, v23, v36
	s_waitcnt lgkmcnt(0)
	v_add_f32_e32 v36, v36, v37
	v_fmamk_f32 v36, v36, 0x3c000000, v170
	v_cmp_gt_f32_e32 vcc, s94, v36
	v_mul_f32_e32 v37, 0x4b800000, v36
	s_nop 0
	v_cndmask_b32_e32 v36, v36, v37, vcc
	v_rsq_f32_e32 v36, v36
	s_nop 0
	v_mul_f32_e32 v37, 0x45800000, v36
	v_cndmask_b32_e32 v36, v36, v37, vcc
	v_pk_mul_f32 v[24:25], v[36:37], v[24:25] op_sel_hi:[0,1]
	v_pk_mul_f32 v[24:25], v[34:35], v[24:25]
	v_mov_b32_e32 v35, v30
	v_pk_mul_f32 v[26:27], v[36:37], v[26:27] op_sel_hi:[0,1]
	v_mov_b32_e32 v30, v29
	v_pk_mul_f32 v[18:19], v[36:37], v[18:19] op_sel_hi:[0,1]
	v_pk_mul_f32 v[32:33], v[36:37], v[32:33] op_sel_hi:[0,1]
	v_mov_b32_e32 v34, v28
	v_pk_mul_f32 v[26:27], v[30:31], v[26:27]
	v_pk_mul_f32 v[18:19], v[38:39], v[18:19]
	v_pk_mul_f32 v[32:33], v[34:35], v[32:33]
	v_bfe_u32 v28, v27, 16, 1
	v_bfe_u32 v29, v26, 16, 1
	v_bfe_u32 v30, v25, 16, 1
	v_bfe_u32 v31, v24, 16, 1
	v_add3_u32 v24, v24, v31, s15
	v_add3_u32 v25, v25, v30, s15
	v_add3_u32 v26, v26, v29, s15
	v_add3_u32 v27, v27, v28, s15
	v_bfe_u32 v28, v18, 16, 1
	v_bfe_u32 v29, v19, 16, 1
	v_bfe_u32 v30, v32, 16, 1
	v_bfe_u32 v31, v33, 16, 1
	v_add3_u32 v31, v33, v31, s15
	v_add3_u32 v30, v32, v30, s15
	v_add3_u32 v19, v19, v29, s15
	v_add3_u32 v18, v18, v28, s15
	v_lshrrev_b32_e32 v18, 16, v18
	v_lshrrev_b32_e32 v19, 16, v19
	v_lshrrev_b32_e32 v28, 16, v30
	v_lshrrev_b32_e32 v29, 16, v31
	v_add_co_u32_e32 v16, vcc, 0x18820000, v16
	v_and_or_b32 v27, v27, s14, v29
	v_and_or_b32 v26, v26, s14, v28
	v_and_or_b32 v25, v25, s14, v19
	v_and_or_b32 v24, v24, s14, v18
	v_addc_co_u32_e32 v17, vcc, 0, v17, vcc
	global_store_dwordx4 v[16:17], v[24:27], off
	s_cbranch_scc1 .LBB0_397
